# v19 + mixer-A edge-tile steps: band masks folded into precomputed MFMA C-init blocks, fully masked halves skipped, no per-step mask VALU
# baseline (speedup 1.0000x reference)
; #define ARGP(i) ka_ptr(ka, (i) * 8)
; template <int MODE, bool FIX> ...
;     const int r32 = lane & 31, hi = lane >> 5;
;     const int b = unit >> 7, rem = unit & 127;
;     int head, qtok, qcol, kcol, vcol, ocol, NTL, lrow0;
;     int s_sub = 0, tl0 = 0;
;     int qrow = 0, qc = 0, kc0 = 0, kr_lo = 0, wa_lo = 0, wa_hi = 0, rs = 0;
;     unsigned colmask = 0u;
;     if (MODE == 0) {
;         const int qblk = rem >> 1, kvh = rem & 1, q0 = qblk * 64;
;         head = kvh * 4 + (wid >> 1); s_sub = wid & 1; qtok = q0 + 32 * s_sub + r32; qcol = head * 64; kcol = 512 + kvh * 64; vcol = 640 + kvh * 64; ocol = head * 64;
;         tl0 = (2 - qblk) > 0 ? (2 - qblk) : 0; const int tl1 = (65 - qblk) < 4 ? (65 - qblk) : 4; NTL = tl1 - tl0 + 1; lrow0 = b * SEQ + q0 - 128 + 64 * tl0;
;     } else {
;         head = rem >> 4; const int r0 = 4 * (rem & 15), rp = wid >> 2, cgp = wid & 3;
;         qrow = r0 + 2 * rp + (r32 >> 4); qc = 16 * cgp + (r32 & 15); qtok = qrow * 64 + qc; qcol = 768 + head * 64; kcol = 1280 + head * 64; vcol = 1792 + head * 64; ocol = 512 + head * 64;
;         kr_lo = (r0 - 4) > 0 ? (r0 - 4) : 0; const int kr_hi = clampi(r0 - 1, 0, 56) + 7; NTL = kr_hi - kr_lo + 1; lrow0 = b * SEQ + kr_lo * 64;
;         kc0 = clampi(16 * cgp - 8, 0, 32); const int cs = clampi(qc - 8, 0, 48);
;         wa_lo = clampi(r0 + 2 * rp - 4, 0, 56); wa_hi = clampi(r0 + 2 * rp - 3, 0, 56) + 7; rs = clampi(qrow - 4, 0, 56);
; #pragma unroll
;         for (int r = 0; r < 16; ++r) { const int kc = kc0 + (r & 3) + 8 * (r >> 2) + 4 * hi; if ((unsigned)(kc - cs) < 16u) colmask |= (1u << r); }
;         LAS float* rt = (LAS float*)(lds + RPB_OFF);
;         if (tid < 465) rt[tid] = rpb[head * 465 + tid] * LOG2E;
;     }
; __global__ void __launch_bounds__(NWAVES * 64, 2) fwd_kernel(Args args_unused) {
;     ...
;     if (IN(3)) for (int rep = 0; rep < NREP(3); ++rep) {
;         GET_LANE();
;         unsigned char* const ws = ARG_WS();
;         const bf16_t* QKV = (const bf16_t*)(ws + WS_QKV); bf16_t* Ob = (bf16_t*)(ws + WS_O); float* ssq1 = (float*)(ws + (FIRST_OF_2(3) ? WS_DUMMY : WS_SSQ1));
;         const float* sinkp = ARGP(I_SINK); const float* rpbp = ARGP(I_RPB);
;         const int per = (1024 + G - 1) / G;
;         const float MA = ((const float*)(ws + WS_BOUNDS))[0], MB = ((const float*)(ws + WS_BOUNDS))[1];
;         const bool fixA = MA < 48.0f, fixB = MB < 48.0f;
.LBB0_568:
	s_cmp_lt_i32 s89, 4
	v_writelane_b32 v255, s94, 2
	s_cselect_b64 s[0:1], -1, 0
	v_writelane_b32 v255, s0, 3
	s_nop 1
	v_writelane_b32 v255, s1, 4
	s_and_b64 s[0:1], s[0:1], s[4:5]
	s_andn2_b64 vcc, exec, s[0:1]
	s_cbranch_vccnz .LBB0_735
	s_abs_i32 s0, s33
	v_cvt_f32_u32_e32 v0, s0
	v_mbcnt_lo_u32_b32 v197, -1, 0
	v_mbcnt_hi_u32_b32 v197, -1, v197
	s_load_dwordx2 s[2:3], s[96:97], 0xb0
	s_waitcnt lgkmcnt(0)
	s_load_dwordx2 s[4:5], s[96:97], 0x50
	s_waitcnt lgkmcnt(0)
	v_rcp_iflag_f32_e32 v0, v0
	v_writelane_b32 v255, s4, 5
	s_load_dwordx2 s[6:7], s[96:97], 0x68
	s_waitcnt lgkmcnt(0)
	s_add_i32 s1, s33, 0x3ff
	v_mul_f32_e32 v0, 0x4f7ffffe, v0
	v_cvt_u32_f32_e32 v0, v0
	v_writelane_b32 v255, s5, 6
	v_writelane_b32 v255, s6, 7
	s_sub_i32 s5, 0, s0
	s_xor_b32 s4, s1, s33
	v_writelane_b32 v255, s7, 8
	v_readfirstlane_b32 s6, v0
	s_mul_i32 s5, s5, s6
	s_mul_hi_u32 s5, s6, s5
	s_abs_i32 s1, s1
	s_add_i32 s6, s6, s5
	s_mul_hi_u32 s5, s1, s6
	s_mul_i32 s6, s5, s0
	s_sub_i32 s1, s1, s6
	s_ashr_i32 s4, s4, 31
	s_add_i32 s6, s5, 1
	s_sub_i32 s7, s1, s0
	s_cmp_ge_u32 s1, s0
	s_cselect_b32 s5, s6, s5
	s_cselect_b32 s1, s7, s1
	s_add_i32 s6, s5, 1
	s_cmp_ge_u32 s1, s0
	s_cselect_b32 s0, s6, s5
	s_xor_b32 s0, s0, s4
	s_sub_i32 s94, s0, s4
	s_cmp_lt_i32 s94, 1
	s_mov_b32 s87, 0
	s_cbranch_scc1 .LBB0_735
	v_mov_b32_e32 v0, 0xc3000
	global_load_dwordx2 v[182:183], v0, s[2:3]
	v_writelane_b32 v255, s56, 0
	v_writelane_b32 v255, s92, 9
	v_add_u32_e32 v188, s71, v197
	v_and_b32_e32 v0, 7, v197
	v_writelane_b32 v255, s93, 10
	v_writelane_b32 v255, s83, 11
	v_writelane_b32 v255, s82, 12
	v_writelane_b32 v255, s90, 13
	v_writelane_b32 v255, s89, 14
	v_writelane_b32 v255, s96, 15
	s_movk_i32 s4, 0x90
	v_lshlrev_b32_e32 v1, 4, v197
	v_writelane_b32 v255, s97, 16
	v_ashrrev_i32_e32 v6, 3, v188
	v_readlane_b32 s0, v255, 2
	s_mul_i32 s0, s85, s0
	s_add_i32 s42, s60, s0
	v_lshlrev_b32_e32 v0, 4, v0
	v_writelane_b32 v255, s85, 1
	s_and_b64 s[0:1], s[18:19], exec
	v_mad_u64_u32 v[178:179], s[0:1], v6, s4, v[0:1]
	v_writelane_b32 v255, s71, 17
	v_ashrrev_i32_e32 v2, 5, v197
	s_cselect_b32 s1, s42, s64
	s_lshr_b32 s85, s95, 7
	s_bfe_u32 s74, s95, 0x10006
	v_lshlrev_b32_e32 v3, 1, v197
	v_lshlrev_b32_e32 v198, 2, v2
	v_writelane_b32 v255, s95, 18
	s_add_u32 s0, s2, 0x6400000
	v_and_b32_e32 v196, 31, v197
	v_lshlrev_b32_e32 v176, 3, v2
	v_lshlrev_b32_e32 v189, 4, v2
	v_lshlrev_b32_e32 v190, 8, v2
	v_and_b32_e32 v191, 32, v3
	v_or_b32_e32 v2, 2, v198
	v_or_b32_e32 v3, 3, v198
	v_writelane_b32 v255, s1, 19
	s_mul_i32 s96, s94, s1
	s_addc_u32 s1, s3, 0
	s_movk_i32 s53, 0x1200
	v_cmp_gt_i32_e64 s[42:43], v2, v196
	v_cmp_gt_i32_e64 s[44:45], v3, v196
	v_cmp_lt_i32_e64 s[48:49], v2, v196
	v_cmp_lt_i32_e64 s[50:51], v3, v196
	s_add_u32 s78, s2, 0x10000000
	v_writelane_b32 v255, s0, 20
	s_addc_u32 s79, s3, 0
	s_mov_b32 s52, 0x42400000
	v_mov_b64_e32 v[2:3], s[0:1]
	v_writelane_b32 v255, s1, 21
	v_mad_i64_i32 v[2:3], s[0:1], v6, s53, v[2:3]
	s_add_u32 s0, s2, 0x40000
	s_addc_u32 s1, s3, 0
	v_writelane_b32 v255, s0, 22
	v_lshlrev_b32_e32 v5, 3, v197
	v_and_b32_e32 v7, 48, v1
	v_writelane_b32 v255, s1, 23
	v_and_b32_e32 v192, 24, v5
	v_lshlrev_b32_e32 v5, 6, v6
	v_and_b32_e32 v193, 0xc0, v1
	v_bfe_u32 v199, v197, 2, 2
	v_mov_b32_e32 v1, 0
	v_bfe_u32 v4, v197, 2, 1
	v_lshl_add_u64 v[180:181], v[2:3], 0, v[0:1]
	v_or_b32_e32 v0, v7, v5
	v_lshlrev_b32_e32 v195, 6, v199
	v_subrev_u32_e32 v16, 24, v196
	v_add_u32_e32 v8, -8, v196
	v_add_u32_e32 v9, -9, v196
	v_add_u32_e32 v10, -10, v196
	v_add_u32_e32 v11, -11, v196
	v_add_u32_e32 v12, -16, v196
	v_subrev_u32_e32 v13, 17, v196
	v_subrev_u32_e32 v14, 18, v196
	v_subrev_u32_e32 v15, 19, v196
	v_subrev_u32_e32 v17, 25, v196
	s_waitcnt vmcnt(0)
; template <int MODE, bool FIX> ...
;     ...
;     float m = FIX ? Mb : -INFINITY, l = 0.f;
;     const float ci = FIX ? -Mb : 0.f;
;     const f32x16 cinit = {ci, ci, ci, ci, ci, ci, ci, ci, ci, ci, ci, ci, ci, ci, ci, ci};
;     ...
;             ATT_STEP_PRE(i)
;             if (MODE == 0) {
;                 const int tl = ATT_SEQ_TL(i); const int dA = 2 * tl - s_sub, dB = dA + 1;
;                 const int a0 = (dA < 0 || dA > 8) ? 99 : (dA == 0 ? 0 : -99), b0 = (dA < 0 || dA > 8) ? -99 : (dA == 8 ? 0 : 99);
;                 const int a1 = (dB < 0 || dB > 8) ? 99 : (dB == 0 ? 0 : -99), b1 = (dB < 0 || dB > 8) ? -99 : (dB == 8 ? 0 : 99);
;                 tile64<true>(buf, qf, o0, o1, l, lane, r32, hi, cinit, a0, b0, a1, b1);
	v_cmp_ngt_f32_e64 s[0:1], s52, v182
	v_subrev_u32_e32 v18, 26, v196
	v_subrev_u32_e32 v19, 27, v196
	v_writelane_b32 v255, s0, 24
	v_cmp_gt_i32_e64 s[24:25], v198, v16
	v_or_b32_e32 v20, 1, v198
	v_writelane_b32 v255, s1, 25
	v_cmp_gt_u32_e64 s[0:1], 32, v197
	v_cmp_lt_i32_e64 s[62:63], v198, v16
	v_mul_u32_u24_e32 v179, 0x90, v196
	v_writelane_b32 v255, s0, 26
	v_xor_b32_e32 v16, 0x80000000, v182
	v_sub_u32_e32 v201, v198, v196
	v_writelane_b32 v255, s1, 27
	s_movk_i32 s0, 0x1040
	v_mad_u32_u24 v194, v4, s0, v0
	v_or_b32_e32 v0, v190, v195
	s_sub_i32 s1, 0, s74
	v_or3_b32 v0, v0, v191, v192
	v_writelane_b32 v255, s1, 28
	v_add_u32_e32 v217, 0, v0
	v_mad_u32_u24 v0, v4, s0, v5
	v_or_b32_e32 v0, v0, v7
	v_writelane_b32 v255, s78, 29
	v_add_u32_e32 v0, 0, v0
	v_ashrrev_i32_e32 v177, 31, v176
	v_writelane_b32 v255, s79, 30
	v_cmp_gt_i32_e64 s[4:5], v198, v196
	v_cmp_lt_i32_e64 s[6:7], v198, v196
	v_cmp_gt_i32_e64 s[8:9], v198, v8
	v_cmp_gt_i32_e64 s[10:11], v198, v9
	v_cmp_gt_i32_e64 s[12:13], v198, v10
	v_cmp_gt_i32_e64 s[14:15], v198, v11
	v_cmp_gt_i32_e64 s[16:17], v198, v12
	v_cmp_gt_i32_e64 s[18:19], v198, v13
	v_cmp_gt_i32_e64 s[20:21], v198, v14
	v_cmp_gt_i32_e64 s[22:23], v198, v15
	v_cmp_gt_i32_e64 s[26:27], v198, v17
	v_cmp_gt_i32_e64 s[28:29], v198, v18
	v_cmp_gt_i32_e64 s[30:31], v198, v19
	v_cmp_lt_i32_e64 s[34:35], v198, v8
	v_cmp_lt_i32_e64 s[36:37], v198, v9
	v_cmp_lt_i32_e64 s[38:39], v198, v10
	v_cmp_lt_i32_e64 s[40:41], v198, v11
	v_cmp_lt_i32_e64 s[46:47], v20, v196
	v_lshl_or_b32 v242, s74, 5, v196
	v_cmp_lt_i32_e64 s[54:55], v198, v12
	v_cmp_lt_i32_e64 s[56:57], v198, v13
	v_cmp_lt_i32_e64 s[58:59], v198, v14
	v_cmp_lt_i32_e64 s[60:61], v198, v15
	v_cmp_lt_i32_e64 s[64:65], v198, v17
	v_cmp_lt_i32_e64 s[66:67], v198, v18
	v_cmp_lt_i32_e64 s[68:69], v198, v19
	v_mov_b32_e32 v17, v16
	v_mov_b32_e32 v18, v16
	v_mov_b32_e32 v19, v16
	v_mov_b32_e32 v20, v16
	v_mov_b32_e32 v21, v16
	v_mov_b32_e32 v22, v16
	v_mov_b32_e32 v23, v16
	v_mov_b32_e32 v24, v16
	v_mov_b32_e32 v25, v16
	v_mov_b32_e32 v26, v16
	v_mov_b32_e32 v27, v16
	v_mov_b32_e32 v28, v16
	v_mov_b32_e32 v29, v16
	v_mov_b32_e32 v30, v16
	v_mov_b32_e32 v31, v16
	v_add_u32_e32 v202, 1, v201
	v_add_u32_e32 v203, 2, v201
	v_add_u32_e32 v204, 3, v201
	v_add_u32_e32 v205, 8, v201
	v_add_u32_e32 v206, 9, v201
	v_add_u32_e32 v207, 10, v201
	v_add_u32_e32 v208, 11, v201
	v_add_u32_e32 v209, 16, v201
	v_add_u32_e32 v210, 17, v201
	v_add_u32_e32 v211, 18, v201
	v_add_u32_e32 v212, 19, v201
	v_add_u32_e32 v213, 24, v201
	v_add_u32_e32 v214, 25, v201
	v_add_u32_e32 v215, 26, v201
	v_add_u32_e32 v216, 27, v201
	v_add_u32_e32 v218, 0x2400, v0
	v_add3_u32 v219, v179, v189, 0
	v_add_u32_e32 v220, 0, v178
	s_mov_b32 s76, 0xff800000
	v_mov_b32_e32 v221, 0x1200
	v_mov_b32_e32 v222, 0xff800000
	v_mov_b32_e32 v223, 0x63
	v_mov_b32_e32 v224, 0xffffff9d
	s_mov_b32 s73, s96
	s_mov_b32 s95, 0
	v_writelane_b32 v255, s85, 31
	v_cmp_gt_i32_e32 vcc, 0, v201
	s_nop 1
	v_cndmask_b32_e32 v226, v16, v222, vcc
	v_cmp_gt_i32_e32 vcc, 0, v202
	s_nop 1
	v_cndmask_b32_e32 v227, v16, v222, vcc
	v_cmp_gt_i32_e32 vcc, 0, v203
	s_nop 1
	v_cndmask_b32_e32 v228, v16, v222, vcc
	v_cmp_gt_i32_e32 vcc, 0, v204
	s_nop 1
	v_cndmask_b32_e32 v229, v16, v222, vcc
	v_cmp_gt_i32_e32 vcc, 0, v205
	s_nop 1
	v_cndmask_b32_e32 v230, v16, v222, vcc
	v_cmp_gt_i32_e32 vcc, 0, v206
	s_nop 1
	v_cndmask_b32_e32 v231, v16, v222, vcc
	v_cmp_gt_i32_e32 vcc, 0, v207
	s_nop 1
	v_cndmask_b32_e32 v232, v16, v222, vcc
	v_cmp_gt_i32_e32 vcc, 0, v208
	s_nop 1
	v_cndmask_b32_e32 v233, v16, v222, vcc
	v_cmp_gt_i32_e32 vcc, 0, v209
	s_nop 1
	v_cndmask_b32_e32 v234, v16, v222, vcc
	v_cmp_gt_i32_e32 vcc, 0, v210
	s_nop 1
	v_cndmask_b32_e32 v235, v16, v222, vcc
	v_cmp_gt_i32_e32 vcc, 0, v211
	s_nop 1
	v_cndmask_b32_e32 v236, v16, v222, vcc
	v_cmp_gt_i32_e32 vcc, 0, v212
	s_nop 1
	v_cndmask_b32_e32 v237, v16, v222, vcc
	v_cmp_gt_i32_e32 vcc, 0, v213
	s_nop 1
	v_cndmask_b32_e32 v238, v16, v222, vcc
	v_cmp_gt_i32_e32 vcc, 0, v214
	s_nop 1
	v_cndmask_b32_e32 v239, v16, v222, vcc
	v_cmp_gt_i32_e32 vcc, 0, v215
	s_nop 1
	v_cndmask_b32_e32 v240, v16, v222, vcc
	v_cmp_gt_i32_e32 vcc, 0, v216
	s_nop 1
	v_cndmask_b32_e32 v241, v16, v222, vcc
	v_cmp_lt_i32_e32 vcc, 0, v201
	s_nop 1
	v_cndmask_b32_e32 v200, v16, v222, vcc
	v_cmp_lt_i32_e32 vcc, 0, v202
	s_nop 1
	v_cndmask_b32_e32 v201, v16, v222, vcc
	v_cmp_lt_i32_e32 vcc, 0, v203
	s_nop 1
	v_cndmask_b32_e32 v202, v16, v222, vcc
	v_cmp_lt_i32_e32 vcc, 0, v204
	s_nop 1
	v_cndmask_b32_e32 v203, v16, v222, vcc
	v_cmp_lt_i32_e32 vcc, 0, v205
	s_nop 1
	v_cndmask_b32_e32 v204, v16, v222, vcc
	v_cmp_lt_i32_e32 vcc, 0, v206
	s_nop 1
	v_cndmask_b32_e32 v205, v16, v222, vcc
	v_cmp_lt_i32_e32 vcc, 0, v207
	s_nop 1
	v_cndmask_b32_e32 v206, v16, v222, vcc
	v_cmp_lt_i32_e32 vcc, 0, v208
	s_nop 1
	v_cndmask_b32_e32 v207, v16, v222, vcc
	v_cmp_lt_i32_e32 vcc, 0, v209
	s_nop 1
	v_cndmask_b32_e32 v208, v16, v222, vcc
	v_cmp_lt_i32_e32 vcc, 0, v210
	s_nop 1
	v_cndmask_b32_e32 v209, v16, v222, vcc
	v_cmp_lt_i32_e32 vcc, 0, v211
	s_nop 1
	v_cndmask_b32_e32 v210, v16, v222, vcc
	v_cmp_lt_i32_e32 vcc, 0, v212
	s_nop 1
	v_cndmask_b32_e32 v211, v16, v222, vcc
	v_cmp_lt_i32_e32 vcc, 0, v213
	s_nop 1
	v_cndmask_b32_e32 v212, v16, v222, vcc
	v_cmp_lt_i32_e32 vcc, 0, v214
	s_nop 1
	v_cndmask_b32_e32 v213, v16, v222, vcc
	v_cmp_lt_i32_e32 vcc, 0, v215
	s_nop 1
	v_cndmask_b32_e32 v214, v16, v222, vcc
	v_cmp_lt_i32_e32 vcc, 0, v216
	s_nop 1
	v_cndmask_b32_e32 v215, v16, v222, vcc
	s_branch .LBB0_573

; #define LAS __attribute__((address_space(3)))
; template <int MODE, bool FIX> ...
;     ...
;     const int b = unit >> 7, rem = unit & 127;
;     int head, qtok, qcol, kcol, vcol, ocol, NTL, lrow0;
;     int s_sub = 0, tl0 = 0;
;     int qrow = 0, qc = 0, kc0 = 0, kr_lo = 0, wa_lo = 0, wa_hi = 0, rs = 0;
;     unsigned colmask = 0u;
;     if (MODE == 0) {
;         const int qblk = rem >> 1, kvh = rem & 1, q0 = qblk * 64;
;         head = kvh * 4 + (wid >> 1); s_sub = wid & 1; qtok = q0 + 32 * s_sub + r32; qcol = head * 64; kcol = 512 + kvh * 64; vcol = 640 + kvh * 64; ocol = head * 64;
;         tl0 = (2 - qblk) > 0 ? (2 - qblk) : 0; const int tl1 = (65 - qblk) < 4 ? (65 - qblk) : 4; NTL = tl1 - tl0 + 1; lrow0 = b * SEQ + q0 - 128 + 64 * tl0;
;     } else {
;         head = rem >> 4; const int r0 = 4 * (rem & 15), rp = wid >> 2, cgp = wid & 3;
;         qrow = r0 + 2 * rp + (r32 >> 4); qc = 16 * cgp + (r32 & 15); qtok = qrow * 64 + qc; qcol = 768 + head * 64; kcol = 1280 + head * 64; vcol = 1792 + head * 64; ocol = 512 + head * 64;
;         kr_lo = (r0 - 4) > 0 ? (r0 - 4) : 0; const int kr_hi = clampi(r0 - 1, 0, 56) + 7; NTL = kr_hi - kr_lo + 1; lrow0 = b * SEQ + kr_lo * 64;
;         kc0 = clampi(16 * cgp - 8, 0, 32); const int cs = clampi(qc - 8, 0, 48);
;         wa_lo = clampi(r0 + 2 * rp - 4, 0, 56); wa_hi = clampi(r0 + 2 * rp - 3, 0, 56) + 7; rs = clampi(qrow - 4, 0, 56);
; #pragma unroll
;         for (int r = 0; r < 16; ++r) { const int kc = kc0 + (r & 3) + 8 * (r >> 2) + 4 * hi; if ((unsigned)(kc - cs) < 16u) colmask |= (1u << r); }
;         LAS float* rt = (LAS float*)(lds + RPB_OFF);
;         if (tid < 465) rt[tid] = rpb[head * 465 + tid] * LOG2E;
;     }
;     const int NT = NTL + 4, crow0 = ML + b * CTXL;
;     const LAS float* rpbl = (const LAS float*)(lds + RPB_OFF);
;     bf16x8 qf[4];
;     { const bf16_t* qp = QKV + (size_t)(b * SEQ + qtok) * INC + qcol + hi * 8;
; #pragma unroll
;       for (int d0 = 0; d0 < 4; ++d0) qf[d0] = *(const bf16x8*)(qp + d0 * 16); }
;     float m = FIX ? Mb : -INFINITY, l = 0.f;
;     const float ci = FIX ? -Mb : 0.f;
;     const f32x16 cinit = {ci, ci, ci, ci, ci, ci, ci, ci, ci, ci, ci, ci, ci, ci, ci, ci};
;     f32x16 o0 = {0.f, 0.f, 0.f, 0.f, 0.f, 0.f, 0.f, 0.f, 0.f, 0.f, 0.f, 0.f, 0.f, 0.f, 0.f, 0.f}, o1 = o0;
;     ...
;         u32x4 kA, vA;
.LBB0_573:
	s_add_i32 s0, s95, s96
	s_cmpk_gt_i32 s0, 0x3ff
	s_cbranch_scc1 .LBB0_572
	s_and_b32 s97, s0, 1
	s_ashr_i32 s75, s0, 7
	s_bfe_u32 s72, s0, 0x60001
	s_lshl_b32 s93, s97, 2
	v_readlane_b32 s0, v255, 24
	s_bfe_u32 s91, s73, 0x60001
	s_lshl_b32 s83, s72, 6
	s_add_i32 s93, s93, s85
	v_readlane_b32 s1, v255, 25
	s_sub_i32 s80, 2, s91
	v_or_b32_e32 v225, s83, v242
	s_lshl_b32 s81, s93, 6
	s_sub_i32 s90, 2, s72
	s_mov_b64 s[70:71], -1
	s_and_b64 vcc, exec, s[0:1]
	s_cbranch_vccz .LBB0_655
	v_writelane_b32 v255, s80, 32
	s_max_i32 s0, s80, 0
	s_lshl_b32 s70, s0, 1
	v_readlane_b32 s1, v255, 28
	s_add_i32 s52, s1, s70
	s_sub_i32 s1, 0x41, s91
	s_min_u32 s1, s1, 4
	s_sub_i32 s0, s1, s0
	s_lshl_b32 s0, s0, 1
	s_add_i32 s0, s0, 12
	s_and_b32 s53, s0, -4
	s_sub_i32 s0, 0x41, s72
	s_min_u32 s71, s0, 4
	s_lshl_b32 s0, s75, 12
	s_or_b32 s92, s83, s0
	v_or_b32_e32 v184, s0, v225
	v_readlane_b32 s0, v255, 20
	v_readlane_b32 s1, v255, 21
	s_max_i32 s84, s90, 0
	s_addk_i32 s92, 0xff80
	v_mov_b64_e32 v[2:3], s[0:1]
	s_movk_i32 s0, 0x1200
	v_mad_i64_i32 v[2:3], s[0:1], v184, s0, v[2:3]
	s_lshl_b32 s0, s84, 6
	s_sub_i32 s85, s71, s84
	s_lshl_b32 s78, s75, 8
	s_lshl_b32 s86, s97, 7
	s_add_i32 s77, s92, s0
	s_not_b32 s2, s85
	s_add_i32 s3, s85, 5
	s_add_i32 s78, s78, 0x8000
	v_lshl_add_u64 v[186:187], v[180:181], 0, s[86:87]
	s_lshl_b32 s86, s81, 1
	s_add_i32 s0, s77, 64
	v_lshl_add_u64 v[2:3], v[2:3], 0, s[86:87]
	s_cmp_eq_u32 s90, s71
	v_lshl_add_u64 v[2:3], v[176:177], 1, v[2:3]
	s_cselect_b32 s0, s78, s0
	global_load_dwordx4 v[144:147], v[2:3], off offset:96
	global_load_dwordx4 v[148:151], v[2:3], off offset:64
	global_load_dwordx4 v[152:155], v[2:3], off offset:32
	global_load_dwordx4 v[156:159], v[2:3], off
	v_mad_i64_i32 v[2:3], s[0:1], s0, v221, v[186:187]
	global_load_dwordx4 v[160:163], v[2:3], off offset:1280
	global_load_dwordx4 v[164:167], v[2:3], off offset:1024
	v_mad_i64_i32 v[2:3], s[0:1], s77, v221, v[186:187]
	global_load_dwordx4 v[168:171], v[2:3], off offset:1280
	global_load_dwordx4 v[172:175], v[2:3], off offset:1024
	v_mov_b32_e32 v14, v1
	v_mov_b32_e32 v15, v1
	s_not_b32 s80, s70
	v_mov_b32_e32 v0, v1
	v_mov_b32_e32 v2, v1
	v_mov_b32_e32 v3, v1
	v_mov_b32_e32 v4, v1
	v_mov_b32_e32 v5, v1
	v_mov_b32_e32 v6, v1
	v_mov_b32_e32 v7, v1
	v_mov_b32_e32 v8, v1
	v_mov_b32_e32 v9, v1
	v_mov_b32_e32 v10, v1
	v_mov_b32_e32 v11, v1
	v_mov_b32_e32 v12, v1
	v_mov_b32_e32 v13, v1
	v_mov_b64_e32 v[62:63], v[14:15]
	v_mov_b64_e32 v[46:47], v[14:15]
	v_writelane_b32 v255, s81, 33
	s_mov_b32 s79, 0
	v_ashrrev_i32_e32 v185, 31, v184
	s_add_i32 s80, s80, s74
	v_mov_b32_e32 v227, 0
	v_mov_b32_e32 v226, 0xff800000
	s_mov_b32 s81, 3
	s_mov_b32 s77, 0
	v_mov_b64_e32 v[60:61], v[12:13]
	v_mov_b64_e32 v[58:59], v[10:11]
	v_mov_b64_e32 v[56:57], v[8:9]
	v_mov_b64_e32 v[54:55], v[6:7]
	v_mov_b64_e32 v[52:53], v[4:5]
	v_mov_b64_e32 v[50:51], v[2:3]
	v_mov_b64_e32 v[48:49], v[0:1]
	v_mov_b64_e32 v[44:45], v[12:13]
	v_mov_b64_e32 v[42:43], v[10:11]
	v_mov_b64_e32 v[40:41], v[8:9]
	v_mov_b64_e32 v[38:39], v[6:7]
	v_mov_b64_e32 v[36:37], v[4:5]
	v_mov_b64_e32 v[34:35], v[2:3]
	v_mov_b64_e32 v[32:33], v[0:1]
	s_branch .LBB0_578

; template <bool MASKED>
; __device__ __forceinline__ void tile64(const LAS unsigned char* buf, const bf16x8 (&qf)[4], f32x16& o0, f32x16& o1, float& l, int lane, int r32, int hi, const f32x16& cinit,
;                                        int a0, int b0, int a1, int b1) {
;     ...
;     const LAS unsigned char* kp = buf + r32 * KSTR + hi * 16;
;     const LAS unsigned char* vp = buf + K_BYTES + (4 * hi + ((lane & 15) >> 2)) * 64 + 32 * ((lane >> 4) & 1) + 8 * (lane & 3);
;     const int dq = 4 * hi - r32; const float NEG = -INFINITY;
;     bf16x8 kf0[4], kf1[4];
; #pragma unroll
;     for (int d0 = 0; d0 < 4; ++d0) { kf0[d0] = *(const LAS bf16x8*)(kp + d0 * 32); kf1[d0] = *(const LAS bf16x8*)(kp + 32 * KSTR + d0 * 32); }
;     T64_SB();
;     f32x16 s0 = cinit, s1 = cinit;
; #pragma unroll
;     for (int d0 = 0; d0 < 4; ++d0) s0 = __builtin_amdgcn_mfma_f32_32x32x16_bf16(kf0[d0], qf[d0], s0, 0, 0, 0);
;     s16x4 va[2][8];
; #pragma unroll
;     for (int dh = 0; dh < 2; ++dh)
; #pragma unroll
;         for (int j = 0; j < 8; ++j) va[dh][j] = vtr(vp + dh * V_HALF + j * 512);
;     T64_SB();
; #pragma unroll
;     for (int d0 = 0; d0 < 4; ++d0) {
;         s1 = __builtin_amdgcn_mfma_f32_32x32x16_bf16(kf1[d0], qf[d0], s1, 0, 0, 0);
; #pragma unroll
;         for (int r = 4 * d0; r < 4 * d0 + 4; ++r) { if (MASKED) { const int t = (r & 3) + 8 * (r >> 2) + dq; if (t < a0 || t > b0) s0[r] = NEG; } s0[r] = __builtin_amdgcn_exp2f(s0[r]); }
;         T64_SB();
;     }
;     u32x4 w00, w01;
;     w00.x = cvtpk(s0[0], s0[1]); w00.y = cvtpk(s0[2], s0[3]); w00.z = cvtpk(s0[4], s0[5]); w00.w = cvtpk(s0[6], s0[7]);
;     w01.x = cvtpk(s0[8], s0[9]); w01.y = cvtpk(s0[10], s0[11]); w01.z = cvtpk(s0[12], s0[13]); w01.w = cvtpk(s0[14], s0[15]);
;     const bf16x8 p00 = __builtin_bit_cast(bf16x8, w00), p01 = __builtin_bit_cast(bf16x8, w01);
;     l += (((s0[0] + s0[1]) + (s0[2] + s0[3])) + ((s0[4] + s0[5]) + (s0[6] + s0[7]))) + (((s0[8] + s0[9]) + (s0[10] + s0[11])) + ((s0[12] + s0[13]) + (s0[14] + s0[15])));
;     ...
;     T64_SB();
;     o0 = __builtin_amdgcn_mfma_f32_32x32x16_bf16(T64_VF(0, 0), p00, o0, 0, 0, 0); T64_EXP1(0);  T64_SB();
;     o1 = __builtin_amdgcn_mfma_f32_32x32x16_bf16(T64_VF(1, 0), p00, o1, 0, 0, 0); T64_EXP1(4);  T64_SB();
;     o0 = __builtin_amdgcn_mfma_f32_32x32x16_bf16(T64_VF(0, 1), p01, o0, 0, 0, 0); T64_EXP1(8);  T64_SB();
.LBB0_658:
	s_add_i32 s80, s70, 1
	s_cmp_lt_u32 s70, s77
	v_add_u32_e32 v0, s79, v220
	s_cselect_b32 s70, s78, s1
	s_cmp_lt_u32 s80, s2
	v_add_u32_e32 v10, s79, v218
	s_waitcnt vmcnt(1)
	ds_write_b128 v0, v[2:5]
	s_waitcnt vmcnt(0)
	ds_write_b128 v10, v[6:9]
	s_cselect_b32 s70, s75, s70
	s_waitcnt lgkmcnt(0)
	s_barrier
	v_mad_i64_i32 v[6:7], s[70:71], s70, v221, v[130:131]
	global_load_dwordx4 v[2:5], v[6:7], off offset:1024
	s_nop 0
	global_load_dwordx4 v[6:9], v[6:7], off offset:1280
	v_add_u32_e32 v0, s79, v219
	s_cmp_eq_u32 s79, 0
	s_cselect_b64 s[70:71], -1, 0
	s_and_b64 s[70:71], s[88:89], s[70:71]
	s_and_b64 s[70:71], s[70:71], exec
	s_cselect_b32 s81, 0, 8
	s_sub_i32 s82, s81, s74
	v_add_u32_e32 v244, s79, v217
	s_cmp_eq_u32 s82, 0
	s_cbranch_scc1 .Lam_v1
	s_cmp_eq_u32 s82, 7
	s_cbranch_scc1 .Lam_v4
	s_cmp_eq_u32 s82, 8
	s_cbranch_scc1 .Lam_v3
	ds_read_b128 v[108:111], v0 offset:4608
	ds_read_b128 v[112:115], v0 offset:4640
	ds_read_b128 v[116:119], v0 offset:4672
	ds_read_b128 v[120:123], v0 offset:4704
	ds_read_b64_tr_b16 v[132:133], v244 offset:11264
	ds_read_b64_tr_b16 v[134:135], v244 offset:11776
	ds_read_b64_tr_b16 v[136:137], v244 offset:12288
	ds_read_b64_tr_b16 v[138:139], v244 offset:12800
	ds_read_b64_tr_b16 v[152:153], v244 offset:15424
	ds_read_b64_tr_b16 v[154:155], v244 offset:15936
	ds_read_b64_tr_b16 v[156:157], v244 offset:16448
	ds_read_b64_tr_b16 v[158:159], v244 offset:16960
	s_waitcnt lgkmcnt(8)
	v_mfma_f32_32x32x16_bf16 v[64:79], v[108:111], v[92:95], v[226:241]
	v_mfma_f32_32x32x16_bf16 v[64:79], v[112:115], v[96:99], v[64:79]
	v_mfma_f32_32x32x16_bf16 v[64:79], v[116:119], v[100:103], v[64:79]
	v_mfma_f32_32x32x16_bf16 v[64:79], v[120:123], v[104:107], v[64:79]
	s_nop 11
	v_exp_f32_e32 v15, v64
	v_exp_f32_e32 v149, v65
	v_exp_f32_e32 v161, v66
	v_exp_f32_e32 v163, v67
	v_exp_f32_e32 v109, v68
	v_exp_f32_e32 v111, v69
	v_exp_f32_e32 v165, v70
	v_exp_f32_e32 v167, v71
	v_exp_f32_e32 v113, v72
	v_exp_f32_e32 v115, v73
	v_exp_f32_e32 v169, v74
	v_exp_f32_e32 v171, v75
	v_exp_f32_e32 v89, v76
	v_exp_f32_e32 v117, v77
	v_exp_f32_e32 v91, v78
	v_exp_f32_e32 v119, v79
	v_cvt_pk_bf16_f32 v10, v15, v149
	v_cvt_pk_bf16_f32 v11, v161, v163
	v_cvt_pk_bf16_f32 v12, v109, v111
	v_cvt_pk_bf16_f32 v13, v165, v167
	v_cvt_pk_bf16_f32 v64, v113, v115
	v_cvt_pk_bf16_f32 v65, v169, v171
	v_cvt_pk_bf16_f32 v66, v89, v117
	v_cvt_pk_bf16_f32 v67, v91, v119
	s_nop 1
	s_waitcnt lgkmcnt(0)
	v_mfma_f32_32x32x16_bf16 v[32:47], v[132:135], v[10:13], v[32:47]
	v_mfma_f32_32x32x16_bf16 v[48:63], v[152:155], v[10:13], v[48:63]
	v_mfma_f32_32x32x16_bf16 v[32:47], v[136:139], v[64:67], v[32:47]
	v_mfma_f32_32x32x16_bf16 v[48:63], v[156:159], v[64:67], v[48:63]
	v_add_f32_e32 v15, v15, v149
	v_add_f32_e32 v161, v161, v163
	v_add_f32_e32 v109, v109, v111
	v_add_f32_e32 v165, v165, v167
	v_add_f32_e32 v113, v113, v115
	v_add_f32_e32 v169, v169, v171
	v_add_f32_e32 v89, v89, v117
	v_add_f32_e32 v91, v91, v119
	v_add_f32_e32 v15, v15, v161
	v_add_f32_e32 v109, v109, v165
	v_add_f32_e32 v113, v113, v169
	v_add_f32_e32 v89, v89, v91
	v_add_f32_e32 v15, v15, v109
	v_add_f32_e32 v113, v113, v89
	v_add_f32_e32 v15, v15, v113
	v_add_f32_e32 v150, v150, v15
	s_branch .Lam_tail
.Lam_v1:
	ds_read_b128 v[10:13], v0
	ds_read_b128 v[64:67], v0 offset:32
	ds_read_b128 v[108:111], v0 offset:4608
	ds_read_b128 v[112:115], v0 offset:4640
	ds_read_b128 v[68:71], v0 offset:64
	ds_read_b128 v[72:75], v0 offset:96
	ds_read_b128 v[116:119], v0 offset:4672
	ds_read_b128 v[120:123], v0 offset:4704
	s_waitcnt lgkmcnt(7)
	v_mfma_f32_32x32x16_bf16 v[76:91], v[10:13], v[92:95], v[226:241]
	ds_read_b64_tr_b16 v[10:11], v244 offset:9216
	ds_read_b64_tr_b16 v[12:13], v244 offset:9728
	ds_read_b64_tr_b16 v[124:125], v244 offset:10240
	ds_read_b64_tr_b16 v[126:127], v244 offset:10752
	ds_read_b64_tr_b16 v[132:133], v244 offset:11264
	ds_read_b64_tr_b16 v[134:135], v244 offset:11776
	ds_read_b64_tr_b16 v[136:137], v244 offset:12288
	ds_read_b64_tr_b16 v[138:139], v244 offset:12800
	ds_read_b64_tr_b16 v[140:141], v244 offset:13376
	ds_read_b64_tr_b16 v[142:143], v244 offset:13888
	ds_read_b64_tr_b16 v[144:145], v244 offset:14400
	ds_read_b64_tr_b16 v[146:147], v244 offset:14912
	ds_read_b64_tr_b16 v[152:153], v244 offset:15424
	ds_read_b64_tr_b16 v[154:155], v244 offset:15936
	ds_read_b64_tr_b16 v[156:157], v244 offset:16448
	ds_read_b64_tr_b16 v[158:159], v244 offset:16960
	s_waitcnt lgkmcnt(14)
	v_mfma_f32_32x32x16_bf16 v[76:91], v[64:67], v[96:99], v[76:91]
	v_mfma_f32_32x32x16_bf16 v[76:91], v[68:71], v[100:103], v[76:91]
	v_mfma_f32_32x32x16_bf16 v[76:91], v[72:75], v[104:107], v[76:91]
	s_nop 11
	v_exp_f32_e32 v14, v76
	v_exp_f32_e32 v148, v77
	v_exp_f32_e32 v160, v78
	v_exp_f32_e32 v162, v79
	v_mfma_f32_32x32x16_bf16 v[64:79], v[108:111], v[92:95], v[16:31]
	v_exp_f32_e32 v108, v80
	v_exp_f32_e32 v110, v81
	v_exp_f32_e32 v164, v82
	v_exp_f32_e32 v166, v83
	v_mfma_f32_32x32x16_bf16 v[64:79], v[112:115], v[96:99], v[64:79]
	v_exp_f32_e32 v112, v84
	v_exp_f32_e32 v114, v85
	v_exp_f32_e32 v168, v86
	v_exp_f32_e32 v170, v87
	v_mfma_f32_32x32x16_bf16 v[64:79], v[116:119], v[100:103], v[64:79]
	v_exp_f32_e32 v88, v88
	v_exp_f32_e32 v116, v89
	v_exp_f32_e32 v90, v90
	v_exp_f32_e32 v118, v91
	v_mfma_f32_32x32x16_bf16 v[64:79], v[120:123], v[104:107], v[64:79]
	v_cvt_pk_bf16_f32 v80, v14, v148
	v_cvt_pk_bf16_f32 v81, v160, v162
	v_cvt_pk_bf16_f32 v82, v108, v110
	v_cvt_pk_bf16_f32 v83, v164, v166
	v_cvt_pk_bf16_f32 v84, v112, v114
	v_cvt_pk_bf16_f32 v85, v168, v170
	v_cvt_pk_bf16_f32 v86, v88, v116
	v_cvt_pk_bf16_f32 v87, v90, v118
	s_nop 1
	v_mfma_f32_32x32x16_bf16 v[32:47], v[10:13], v[80:83], v[32:47]
	s_nop 2
	v_exp_f32_e32 v15, v64
	v_exp_f32_e32 v149, v65
	v_exp_f32_e32 v161, v66
	v_exp_f32_e32 v163, v67
	s_waitcnt lgkmcnt(6)
; template <bool MASKED>
; __device__ __forceinline__ void tile64(const LAS unsigned char* buf, const bf16x8 (&qf)[4], f32x16& o0, f32x16& o1, float& l, int lane, int r32, int hi, const f32x16& cinit,
;                                        int a0, int b0, int a1, int b1) {
;     ...
;     const LAS unsigned char* kp = buf + r32 * KSTR + hi * 16;
;     const LAS unsigned char* vp = buf + K_BYTES + (4 * hi + ((lane & 15) >> 2)) * 64 + 32 * ((lane >> 4) & 1) + 8 * (lane & 3);
;     const int dq = 4 * hi - r32; const float NEG = -INFINITY;
;     bf16x8 kf0[4], kf1[4];
; #pragma unroll
;     for (int d0 = 0; d0 < 4; ++d0) { kf0[d0] = *(const LAS bf16x8*)(kp + d0 * 32); kf1[d0] = *(const LAS bf16x8*)(kp + 32 * KSTR + d0 * 32); }
;     T64_SB();
;     f32x16 s0 = cinit, s1 = cinit;
; #pragma unroll
;     for (int d0 = 0; d0 < 4; ++d0) s0 = __builtin_amdgcn_mfma_f32_32x32x16_bf16(kf0[d0], qf[d0], s0, 0, 0, 0);
;     s16x4 va[2][8];
; #pragma unroll
;     for (int dh = 0; dh < 2; ++dh)
; #pragma unroll
;         for (int j = 0; j < 8; ++j) va[dh][j] = vtr(vp + dh * V_HALF + j * 512);
;     T64_SB();
; #pragma unroll
;     for (int d0 = 0; d0 < 4; ++d0) {
;         s1 = __builtin_amdgcn_mfma_f32_32x32x16_bf16(kf1[d0], qf[d0], s1, 0, 0, 0);
; #pragma unroll
;         for (int r = 4 * d0; r < 4 * d0 + 4; ++r) { if (MASKED) { const int t = (r & 3) + 8 * (r >> 2) + dq; if (t < a0 || t > b0) s0[r] = NEG; } s0[r] = __builtin_amdgcn_exp2f(s0[r]); }
;         T64_SB();
;     }
;     u32x4 w00, w01;
;     w00.x = cvtpk(s0[0], s0[1]); w00.y = cvtpk(s0[2], s0[3]); w00.z = cvtpk(s0[4], s0[5]); w00.w = cvtpk(s0[6], s0[7]);
;     w01.x = cvtpk(s0[8], s0[9]); w01.y = cvtpk(s0[10], s0[11]); w01.z = cvtpk(s0[12], s0[13]); w01.w = cvtpk(s0[14], s0[15]);
;     const bf16x8 p00 = __builtin_bit_cast(bf16x8, w00), p01 = __builtin_bit_cast(bf16x8, w01);
;     l += (((s0[0] + s0[1]) + (s0[2] + s0[3])) + ((s0[4] + s0[5]) + (s0[6] + s0[7]))) + (((s0[8] + s0[9]) + (s0[10] + s0[11])) + ((s0[12] + s0[13]) + (s0[14] + s0[15])));
;     ...
;     T64_SB();
;     o0 = __builtin_amdgcn_mfma_f32_32x32x16_bf16(T64_VF(0, 0), p00, o0, 0, 0, 0); T64_EXP1(0);  T64_SB();
;     o1 = __builtin_amdgcn_mfma_f32_32x32x16_bf16(T64_VF(1, 0), p00, o1, 0, 0, 0); T64_EXP1(4);  T64_SB();
;     o0 = __builtin_amdgcn_mfma_f32_32x32x16_bf16(T64_VF(0, 1), p01, o0, 0, 0, 0); T64_EXP1(8);  T64_SB();
	v_mfma_f32_32x32x16_bf16 v[48:63], v[140:143], v[80:83], v[48:63]
	v_exp_f32_e32 v109, v68
	v_exp_f32_e32 v111, v69
	v_exp_f32_e32 v165, v70
	v_exp_f32_e32 v167, v71
	v_mfma_f32_32x32x16_bf16 v[32:47], v[124:127], v[84:87], v[32:47]
	v_exp_f32_e32 v113, v72
	v_exp_f32_e32 v115, v73
	v_exp_f32_e32 v169, v74
	v_exp_f32_e32 v171, v75
	s_waitcnt lgkmcnt(4)
	v_mfma_f32_32x32x16_bf16 v[48:63], v[144:147], v[84:87], v[48:63]
	v_exp_f32_e32 v89, v76
	v_exp_f32_e32 v117, v77
	v_exp_f32_e32 v91, v78
	v_exp_f32_e32 v119, v79
	v_cvt_pk_bf16_f32 v10, v15, v149
	v_cvt_pk_bf16_f32 v11, v161, v163
	v_cvt_pk_bf16_f32 v12, v109, v111
	v_cvt_pk_bf16_f32 v13, v165, v167
	v_pk_add_f32 v[14:15], v[14:15], v[148:149]
	v_pk_add_f32 v[160:161], v[160:161], v[162:163]
	v_mfma_f32_32x32x16_bf16 v[32:47], v[132:135], v[10:13], v[32:47]
	v_cvt_pk_bf16_f32 v64, v113, v115
	v_cvt_pk_bf16_f32 v65, v169, v171
	v_cvt_pk_bf16_f32 v66, v89, v117
	v_cvt_pk_bf16_f32 v67, v91, v119
	v_pk_add_f32 v[108:109], v[108:109], v[110:111]
	v_pk_add_f32 v[164:165], v[164:165], v[166:167]
	s_waitcnt lgkmcnt(2)
	v_mfma_f32_32x32x16_bf16 v[48:63], v[152:155], v[10:13], v[48:63]
	v_pk_add_f32 v[112:113], v[112:113], v[114:115]
	v_pk_add_f32 v[168:169], v[168:169], v[170:171]
	v_pk_add_f32 v[88:89], v[88:89], v[116:117]
	v_pk_add_f32 v[90:91], v[90:91], v[118:119]
	v_pk_add_f32 v[14:15], v[14:15], v[160:161]
	v_pk_add_f32 v[108:109], v[108:109], v[164:165]
	v_mfma_f32_32x32x16_bf16 v[32:47], v[136:139], v[64:67], v[32:47]
	v_pk_add_f32 v[112:113], v[112:113], v[168:169]
	v_pk_add_f32 v[88:89], v[88:89], v[90:91]
	v_pk_add_f32 v[14:15], v[14:15], v[108:109]
	v_pk_add_f32 v[112:113], v[112:113], v[88:89]
	s_waitcnt lgkmcnt(0)
	v_mfma_f32_32x32x16_bf16 v[48:63], v[156:159], v[64:67], v[48:63]
	v_pk_add_f32 v[14:15], v[14:15], v[112:113]
	s_nop 0
	v_add_f32_e32 v0, v150, v14
	v_add_f32_e32 v150, v0, v15
	s_branch .Lam_tail
.Lam_v4:
	ds_read_b128 v[10:13], v0
	ds_read_b128 v[64:67], v0 offset:32
	ds_read_b128 v[108:111], v0 offset:4608
	ds_read_b128 v[112:115], v0 offset:4640
	ds_read_b128 v[68:71], v0 offset:64
	ds_read_b128 v[72:75], v0 offset:96
	ds_read_b128 v[116:119], v0 offset:4672
	ds_read_b128 v[120:123], v0 offset:4704
	s_waitcnt lgkmcnt(7)
	v_mfma_f32_32x32x16_bf16 v[76:91], v[10:13], v[92:95], v[16:31]
	ds_read_b64_tr_b16 v[10:11], v244 offset:9216
	ds_read_b64_tr_b16 v[12:13], v244 offset:9728
	ds_read_b64_tr_b16 v[124:125], v244 offset:10240
	ds_read_b64_tr_b16 v[126:127], v244 offset:10752
	ds_read_b64_tr_b16 v[132:133], v244 offset:11264
	ds_read_b64_tr_b16 v[134:135], v244 offset:11776
	ds_read_b64_tr_b16 v[136:137], v244 offset:12288
	ds_read_b64_tr_b16 v[138:139], v244 offset:12800
	ds_read_b64_tr_b16 v[140:141], v244 offset:13376
	ds_read_b64_tr_b16 v[142:143], v244 offset:13888
	ds_read_b64_tr_b16 v[144:145], v244 offset:14400
	ds_read_b64_tr_b16 v[146:147], v244 offset:14912
	ds_read_b64_tr_b16 v[152:153], v244 offset:15424
	ds_read_b64_tr_b16 v[154:155], v244 offset:15936
	ds_read_b64_tr_b16 v[156:157], v244 offset:16448
	ds_read_b64_tr_b16 v[158:159], v244 offset:16960
	s_waitcnt lgkmcnt(14)
	v_mfma_f32_32x32x16_bf16 v[76:91], v[64:67], v[96:99], v[76:91]
	v_mfma_f32_32x32x16_bf16 v[76:91], v[68:71], v[100:103], v[76:91]
	v_mfma_f32_32x32x16_bf16 v[76:91], v[72:75], v[104:107], v[76:91]
	s_nop 11
	v_exp_f32_e32 v14, v76
	v_exp_f32_e32 v148, v77
	v_exp_f32_e32 v160, v78
	v_exp_f32_e32 v162, v79
	v_mfma_f32_32x32x16_bf16 v[64:79], v[108:111], v[92:95], v[200:215]
	v_exp_f32_e32 v108, v80
	v_exp_f32_e32 v110, v81
	v_exp_f32_e32 v164, v82
	v_exp_f32_e32 v166, v83
	v_mfma_f32_32x32x16_bf16 v[64:79], v[112:115], v[96:99], v[64:79]
	v_exp_f32_e32 v112, v84
	v_exp_f32_e32 v114, v85
	v_exp_f32_e32 v168, v86
	v_exp_f32_e32 v170, v87
	v_mfma_f32_32x32x16_bf16 v[64:79], v[116:119], v[100:103], v[64:79]
	v_exp_f32_e32 v88, v88
	v_exp_f32_e32 v116, v89
	v_exp_f32_e32 v90, v90
	v_exp_f32_e32 v118, v91
	v_mfma_f32_32x32x16_bf16 v[64:79], v[120:123], v[104:107], v[64:79]
	v_cvt_pk_bf16_f32 v80, v14, v148
	v_cvt_pk_bf16_f32 v81, v160, v162
	v_cvt_pk_bf16_f32 v82, v108, v110
	v_cvt_pk_bf16_f32 v83, v164, v166
	v_cvt_pk_bf16_f32 v84, v112, v114
	v_cvt_pk_bf16_f32 v85, v168, v170
	v_cvt_pk_bf16_f32 v86, v88, v116
	v_cvt_pk_bf16_f32 v87, v90, v118
	s_nop 1
	v_mfma_f32_32x32x16_bf16 v[32:47], v[10:13], v[80:83], v[32:47]
	s_nop 2
	v_exp_f32_e32 v15, v64
	v_exp_f32_e32 v149, v65
	v_exp_f32_e32 v161, v66
	v_exp_f32_e32 v163, v67
	s_waitcnt lgkmcnt(6)
	v_mfma_f32_32x32x16_bf16 v[48:63], v[140:143], v[80:83], v[48:63]
	v_exp_f32_e32 v109, v68
	v_exp_f32_e32 v111, v69
	v_exp_f32_e32 v165, v70
	v_exp_f32_e32 v167, v71
	v_mfma_f32_32x32x16_bf16 v[32:47], v[124:127], v[84:87], v[32:47]
	v_exp_f32_e32 v113, v72
	v_exp_f32_e32 v115, v73
	v_exp_f32_e32 v169, v74
	v_exp_f32_e32 v171, v75
	s_waitcnt lgkmcnt(4)
	v_mfma_f32_32x32x16_bf16 v[48:63], v[144:147], v[84:87], v[48:63]
	v_exp_f32_e32 v89, v76
	v_exp_f32_e32 v117, v77
	v_exp_f32_e32 v91, v78
	v_exp_f32_e32 v119, v79
	v_cvt_pk_bf16_f32 v10, v15, v149
	v_cvt_pk_bf16_f32 v11, v161, v163
	v_cvt_pk_bf16_f32 v12, v109, v111
	v_cvt_pk_bf16_f32 v13, v165, v167
	v_pk_add_f32 v[14:15], v[14:15], v[148:149]
	v_pk_add_f32 v[160:161], v[160:161], v[162:163]
	v_mfma_f32_32x32x16_bf16 v[32:47], v[132:135], v[10:13], v[32:47]
	v_cvt_pk_bf16_f32 v64, v113, v115
	v_cvt_pk_bf16_f32 v65, v169, v171
	v_cvt_pk_bf16_f32 v66, v89, v117
	v_cvt_pk_bf16_f32 v67, v91, v119
	v_pk_add_f32 v[108:109], v[108:109], v[110:111]
	v_pk_add_f32 v[164:165], v[164:165], v[166:167]
	s_waitcnt lgkmcnt(2)
	v_mfma_f32_32x32x16_bf16 v[48:63], v[152:155], v[10:13], v[48:63]
	v_pk_add_f32 v[112:113], v[112:113], v[114:115]
	v_pk_add_f32 v[168:169], v[168:169], v[170:171]
	v_pk_add_f32 v[88:89], v[88:89], v[116:117]
	v_pk_add_f32 v[90:91], v[90:91], v[118:119]
	v_pk_add_f32 v[14:15], v[14:15], v[160:161]
	v_pk_add_f32 v[108:109], v[108:109], v[164:165]
	v_mfma_f32_32x32x16_bf16 v[32:47], v[136:139], v[64:67], v[32:47]
	v_pk_add_f32 v[112:113], v[112:113], v[168:169]
	v_pk_add_f32 v[88:89], v[88:89], v[90:91]
	v_pk_add_f32 v[14:15], v[14:15], v[108:109]
	v_pk_add_f32 v[112:113], v[112:113], v[88:89]
	s_waitcnt lgkmcnt(0)
	v_mfma_f32_32x32x16_bf16 v[48:63], v[156:159], v[64:67], v[48:63]
	v_pk_add_f32 v[14:15], v[14:15], v[112:113]
	s_nop 0
	v_add_f32_e32 v0, v150, v14
	v_add_f32_e32 v150, v0, v15
	s_branch .Lam_tail
; template <bool MASKED>
; __device__ __forceinline__ void tile64(const LAS unsigned char* buf, const bf16x8 (&qf)[4], f32x16& o0, f32x16& o1, float& l, int lane, int r32, int hi, const f32x16& cinit,
;                                        int a0, int b0, int a1, int b1) {
;     ...
;     const LAS unsigned char* kp = buf + r32 * KSTR + hi * 16;
;     const LAS unsigned char* vp = buf + K_BYTES + (4 * hi + ((lane & 15) >> 2)) * 64 + 32 * ((lane >> 4) & 1) + 8 * (lane & 3);
;     const int dq = 4 * hi - r32; const float NEG = -INFINITY;
;     bf16x8 kf0[4], kf1[4];
; #pragma unroll
;     for (int d0 = 0; d0 < 4; ++d0) { kf0[d0] = *(const LAS bf16x8*)(kp + d0 * 32); kf1[d0] = *(const LAS bf16x8*)(kp + 32 * KSTR + d0 * 32); }
;     T64_SB();
;     f32x16 s0 = cinit, s1 = cinit;
; #pragma unroll
;     for (int d0 = 0; d0 < 4; ++d0) s0 = __builtin_amdgcn_mfma_f32_32x32x16_bf16(kf0[d0], qf[d0], s0, 0, 0, 0);
;     s16x4 va[2][8];
; #pragma unroll
;     for (int dh = 0; dh < 2; ++dh)
; #pragma unroll
;         for (int j = 0; j < 8; ++j) va[dh][j] = vtr(vp + dh * V_HALF + j * 512);
;     T64_SB();
; #pragma unroll
;     for (int d0 = 0; d0 < 4; ++d0) {
;         s1 = __builtin_amdgcn_mfma_f32_32x32x16_bf16(kf1[d0], qf[d0], s1, 0, 0, 0);
; #pragma unroll
;         for (int r = 4 * d0; r < 4 * d0 + 4; ++r) { if (MASKED) { const int t = (r & 3) + 8 * (r >> 2) + dq; if (t < a0 || t > b0) s0[r] = NEG; } s0[r] = __builtin_amdgcn_exp2f(s0[r]); }
;         T64_SB();
;     }
;     u32x4 w00, w01;
;     w00.x = cvtpk(s0[0], s0[1]); w00.y = cvtpk(s0[2], s0[3]); w00.z = cvtpk(s0[4], s0[5]); w00.w = cvtpk(s0[6], s0[7]);
;     w01.x = cvtpk(s0[8], s0[9]); w01.y = cvtpk(s0[10], s0[11]); w01.z = cvtpk(s0[12], s0[13]); w01.w = cvtpk(s0[14], s0[15]);
;     const bf16x8 p00 = __builtin_bit_cast(bf16x8, w00), p01 = __builtin_bit_cast(bf16x8, w01);
;     l += (((s0[0] + s0[1]) + (s0[2] + s0[3])) + ((s0[4] + s0[5]) + (s0[6] + s0[7]))) + (((s0[8] + s0[9]) + (s0[10] + s0[11])) + ((s0[12] + s0[13]) + (s0[14] + s0[15])));
;     ...
;     T64_SB();
;     o0 = __builtin_amdgcn_mfma_f32_32x32x16_bf16(T64_VF(0, 0), p00, o0, 0, 0, 0); T64_EXP1(0);  T64_SB();
; template <int MODE, bool FIX> ...
;     ...
;         for (; i < nmask; ++i) {
;             ATT_STEP_PRE(i)
;             if (MODE == 0) {
;                 const int tl = ATT_SEQ_TL(i); const int dA = 2 * tl - s_sub, dB = dA + 1;
.Lam_v3:
	ds_read_b128 v[10:13], v0
	ds_read_b128 v[64:67], v0 offset:32
	ds_read_b128 v[68:71], v0 offset:64
	ds_read_b128 v[72:75], v0 offset:96
	s_waitcnt lgkmcnt(3)
	v_mfma_f32_32x32x16_bf16 v[76:91], v[10:13], v[92:95], v[200:215]
	ds_read_b64_tr_b16 v[10:11], v244 offset:9216
	ds_read_b64_tr_b16 v[12:13], v244 offset:9728
	ds_read_b64_tr_b16 v[124:125], v244 offset:10240
	ds_read_b64_tr_b16 v[126:127], v244 offset:10752
	ds_read_b64_tr_b16 v[140:141], v244 offset:13376
	ds_read_b64_tr_b16 v[142:143], v244 offset:13888
	ds_read_b64_tr_b16 v[144:145], v244 offset:14400
	ds_read_b64_tr_b16 v[146:147], v244 offset:14912
	s_waitcnt lgkmcnt(8)
	v_mfma_f32_32x32x16_bf16 v[76:91], v[64:67], v[96:99], v[76:91]
	v_mfma_f32_32x32x16_bf16 v[76:91], v[68:71], v[100:103], v[76:91]
	v_mfma_f32_32x32x16_bf16 v[76:91], v[72:75], v[104:107], v[76:91]
	s_nop 11
	v_exp_f32_e32 v14, v76
	v_exp_f32_e32 v148, v77
	v_exp_f32_e32 v160, v78
	v_exp_f32_e32 v162, v79
	v_exp_f32_e32 v108, v80
	v_exp_f32_e32 v110, v81
	v_exp_f32_e32 v164, v82
	v_exp_f32_e32 v166, v83
	v_exp_f32_e32 v112, v84
	v_exp_f32_e32 v114, v85
	v_exp_f32_e32 v168, v86
	v_exp_f32_e32 v170, v87
	v_exp_f32_e32 v88, v88
	v_exp_f32_e32 v116, v89
	v_exp_f32_e32 v90, v90
	v_exp_f32_e32 v118, v91
	v_cvt_pk_bf16_f32 v80, v14, v148
	v_cvt_pk_bf16_f32 v81, v160, v162
	v_cvt_pk_bf16_f32 v82, v108, v110
	v_cvt_pk_bf16_f32 v83, v164, v166
	v_cvt_pk_bf16_f32 v84, v112, v114
	v_cvt_pk_bf16_f32 v85, v168, v170
	v_cvt_pk_bf16_f32 v86, v88, v116
	v_cvt_pk_bf16_f32 v87, v90, v118
	s_nop 1
	s_waitcnt lgkmcnt(0)
	v_mfma_f32_32x32x16_bf16 v[32:47], v[10:13], v[80:83], v[32:47]
	v_mfma_f32_32x32x16_bf16 v[48:63], v[140:143], v[80:83], v[48:63]
	v_mfma_f32_32x32x16_bf16 v[32:47], v[124:127], v[84:87], v[32:47]
	v_mfma_f32_32x32x16_bf16 v[48:63], v[144:147], v[84:87], v[48:63]
	v_add_f32_e32 v14, v14, v148
	v_add_f32_e32 v160, v160, v162
	v_add_f32_e32 v108, v108, v110
	v_add_f32_e32 v164, v164, v166
	v_add_f32_e32 v112, v112, v114
	v_add_f32_e32 v168, v168, v170
	v_add_f32_e32 v88, v88, v116
	v_add_f32_e32 v90, v90, v118
	v_add_f32_e32 v14, v14, v160
	v_add_f32_e32 v108, v108, v164
	v_add_f32_e32 v112, v112, v168
	v_add_f32_e32 v88, v88, v90
	v_add_f32_e32 v14, v14, v108
	v_add_f32_e32 v112, v112, v88
	v_add_f32_e32 v14, v14, v112
	v_add_f32_e32 v150, v150, v14
.Lam_tail:
	s_addk_i32 s79, 0x4480
	s_add_i32 s78, s78, 64
	s_mul_i32 s71, s2, 0x4480
	s_mov_b32 s70, s80
	s_cmp_eq_u32 s71, s79
	s_cbranch_scc0 .LBB0_658
	s_branch .LBB0_662
